# forgetting-attention phase: second-round unit uses head 15-h so each workgroup pairs two different heads (balances head-dependent early exit)
# speedup vs baseline: 1.0165x; 1.0165x over previous
; #define LAS __attribute__((address_space(3)))
; template <int DQK, bool FOX>
; __device__ __forceinline__ void causal_attn_phase(LAS unsigned char* lds, const bf16_t* Q, int qpitch, const bf16_t* K1, const bf16_t* K2, const bf16_t* V, bf16_t* O, const float* cum2, const float* rope_cs_tab, const float* fox_ct) {
;     ...
;         const int rnd = u >> 8, bb = u & 255, head = bb & 15, qb = rnd == 0 ? 31 - (bb >> 4) : (bb >> 4);
;         const int q0 = qb * 256, qrow = q0 + wid * 32 + r32;
;         bf16x8 qf[NKS];
;         { const bf16_t* qp = Q + (size_t)qrow * qpitch + head * DQK + hi * 8;
; #pragma unroll
;           for (int ks = 0; ks < NKS; ++ks) qf[ks] = *(const bf16x8*)(qp + ks * 16); }
;         if constexpr (DQK == 192) {
; #pragma unroll
;             for (int sidx = 0; sidx < 2; ++sidx) {
;                 const f32x4* csp = (const f32x4*)(rope_cs_tab + (size_t)qrow * 64 + (16 * sidx + 8 * hi) * 2);
; #pragma unroll
;                 for (int jj = 0; jj < 4; ++jj) { const f32x4 cs = csp[jj];
; #pragma unroll
;                     for (int e = 0; e < 2; ++e) { const int j = 2 * jj + e; const float c = e ? cs.z : cs.x, sn = e ? cs.w : cs.y;
;                         const float x1 = bf2f((unsigned short)qf[8 + sidx][j]), x2 = bf2f((unsigned short)qf[10 + sidx][j]);
;                         qf[8 + sidx][j] = (short)(cvtpk(x1 * c - x2 * sn, 0.f) & 0xffffu); qf[10 + sidx][j] = (short)(cvtpk(x2 * c + x1 * sn, 0.f) & 0xffffu); } }
;             }
;         }
;         LAS float* offs = (LAS float*)(lds + 2 * BUF);
;         if constexpr (FOX) {
;             if (wid == 0) { const float a = fox_ct[head * 128 + lane], b = fox_ct[head * 128 + 64 + lane]; float ia = a, ib = b;
; #pragma unroll
;                 for (int o_ = 1; o_ < 64; o_ <<= 1) { const float va = __shfl_up(ia, o_), vb = __shfl_up(ib, o_); if (lane >= o_) { ia += va; ib += vb; } }
;                 const float tota = __shfl(ia, 63);
;                 offs[lane] = ia - a; offs[64 + lane] = tota + (ib - b);
;                 float km = fmaxf(fox_ct[T + head * 128 + lane], fox_ct[T + head * 128 + 64 + lane]);
; #pragma unroll
;                 for (int o_ = 1; o_ < 64; o_ <<= 1) km = fmaxf(km, __shfl_xor(km, o_));
;                 if (lane == 0) { offs[128] = km; offs[132] = 0.f; offs[133] = 0.f; offs[134] = 0.f; offs[135] = 0.f; } }
.LBB0_2744:
	s_lshr_b32 s3, s43, 4
	s_and_b32 s10, s43, 15
	s_sub_i32 s3, 31, s3
	s_bfe_u32 s4, s43, 0x40004
	s_cmpk_lt_u32 s43, 0x100
	s_cselect_b32 s8, s3, s4
	s_cselect_b32 s3, 0, 15
	s_xor_b32 s10, s10, s3
	s_lshl_b32 s9, s8, 8
	s_add_i32 s35, s9, s40
	v_or_b32_e32 v2, s35, v193
	v_ashrrev_i32_e32 v3, 31, v2
	v_lshlrev_b64 v[190:191], 12, v[2:3]
	v_lshl_add_u64 v[2:3], s[30:31], 0, v[190:191]
	s_lshl_b32 s24, s10, 8
	v_lshl_add_u64 v[2:3], v[2:3], 0, s[24:25]
	v_mov_b32_e32 v187, v1
	v_lshl_add_u64 v[2:3], v[2:3], 0, v[186:187]
	global_load_dwordx4 v[128:131], v[2:3], off
	global_load_dwordx4 v[132:135], v[2:3], off offset:32
	global_load_dwordx4 v[136:139], v[2:3], off offset:64
	global_load_dwordx4 v[140:143], v[2:3], off offset:96
	global_load_dwordx4 v[144:147], v[2:3], off offset:128
	global_load_dwordx4 v[148:151], v[2:3], off offset:160
	global_load_dwordx4 v[152:155], v[2:3], off offset:192
	global_load_dwordx4 v[156:159], v[2:3], off offset:224
	v_readlane_b32 s4, v245, 30
	v_readlane_b32 s5, v245, 31
	s_andn2_b64 vcc, exec, s[4:5]
	s_lshl_b32 s3, s10, 7
	s_cbranch_vccnz .LBB0_2748
	v_or_b32_e32 v0, s3, v192
	v_lshlrev_b32_e32 v0, 2, v0
	global_load_dword v4, v0, s[26:27]
	global_load_dword v5, v0, s[26:27] offset:256
	v_lshl_add_u64 v[2:3], s[26:27], 0, v[0:1]
	s_mov_b32 s4, 0x8000
	v_add_co_u32_e32 v2, vcc, s4, v2
	v_readlane_b32 s4, v245, 32
	s_nop 0
	v_addc_co_u32_e32 v3, vcc, 0, v3, vcc
	global_load_dword v0, v[2:3], off offset:256
	s_nop 0
	global_load_dword v2, v[2:3], off
	v_readlane_b32 s5, v245, 33
	s_waitcnt vmcnt(3)
	ds_bpermute_b32 v3, v205, v4
	s_waitcnt vmcnt(2)
	ds_bpermute_b32 v6, v205, v5
	s_waitcnt lgkmcnt(1)
	v_add_f32_e32 v3, v4, v3
	v_cndmask_b32_e64 v3, v3, v4, s[6:7]
	ds_bpermute_b32 v7, v206, v3
	s_waitcnt vmcnt(1)
	v_max_f32_e32 v0, v0, v0
	s_waitcnt vmcnt(0)
	v_max_f32_e32 v2, v2, v2
	v_max_f32_e32 v0, v2, v0
	ds_bpermute_b32 v2, v212, v0
	s_waitcnt lgkmcnt(2)
	v_add_f32_e32 v6, v5, v6
	v_cndmask_b32_e64 v6, v6, v5, s[6:7]
	ds_bpermute_b32 v8, v206, v6
	s_waitcnt lgkmcnt(2)
	v_add_f32_e32 v7, v3, v7
	v_cndmask_b32_e64 v3, v7, v3, s[4:5]
	s_waitcnt lgkmcnt(1)
	v_max_f32_e32 v2, v2, v2
	ds_bpermute_b32 v7, v207, v3
	v_max_f32_e32 v0, v0, v2
	ds_bpermute_b32 v2, v213, v0
	s_waitcnt lgkmcnt(2)
	v_add_f32_e32 v8, v6, v8
	v_cndmask_b32_e64 v6, v8, v6, s[4:5]
	ds_bpermute_b32 v8, v207, v6
	v_readlane_b32 s4, v245, 34
	s_waitcnt lgkmcnt(2)
	v_add_f32_e32 v7, v3, v7
	v_readlane_b32 s5, v245, 35
	s_waitcnt lgkmcnt(1)
	v_max_f32_e32 v2, v2, v2
	v_max_f32_e32 v0, v0, v2
	v_cndmask_b32_e64 v3, v7, v3, s[4:5]
	ds_bpermute_b32 v7, v208, v3
	ds_bpermute_b32 v2, v214, v0
	s_waitcnt lgkmcnt(2)
	v_add_f32_e32 v8, v6, v8
	v_cndmask_b32_e64 v6, v8, v6, s[4:5]
	ds_bpermute_b32 v8, v208, v6
	v_readlane_b32 s4, v245, 36
	s_waitcnt lgkmcnt(2)
	v_add_f32_e32 v7, v3, v7
	v_readlane_b32 s5, v245, 37
	s_waitcnt lgkmcnt(1)
	v_max_f32_e32 v2, v2, v2
	v_max_f32_e32 v0, v0, v2
	v_cndmask_b32_e64 v3, v7, v3, s[4:5]
	ds_bpermute_b32 v7, v209, v3
	ds_bpermute_b32 v2, v215, v0
	s_waitcnt lgkmcnt(2)
	v_add_f32_e32 v8, v6, v8
	v_cndmask_b32_e64 v6, v8, v6, s[4:5]
	ds_bpermute_b32 v8, v209, v6
	s_waitcnt lgkmcnt(2)
	v_add_f32_e32 v7, v3, v7
	v_cndmask_b32_e64 v3, v7, v3, s[52:53]
	s_waitcnt lgkmcnt(1)
	v_max_f32_e32 v2, v2, v2
	ds_bpermute_b32 v7, v210, v3
	v_max_f32_e32 v0, v0, v2
	ds_bpermute_b32 v2, v216, v0
	s_waitcnt lgkmcnt(2)
	v_add_f32_e32 v8, v6, v8
	v_cndmask_b32_e64 v6, v8, v6, s[52:53]
	ds_bpermute_b32 v8, v210, v6
	s_waitcnt lgkmcnt(2)
	v_add_f32_e32 v7, v3, v7
	v_cndmask_b32_e64 v3, v7, v3, s[54:55]
	s_waitcnt lgkmcnt(1)
	v_max_f32_e32 v2, v2, v2
	ds_bpermute_b32 v7, v211, v3
	v_max_f32_e32 v0, v0, v2
	ds_bpermute_b32 v2, v195, v0
	s_waitcnt lgkmcnt(2)
	v_add_f32_e32 v8, v6, v8
	v_cndmask_b32_e64 v6, v8, v6, s[54:55]
	v_sub_f32_e32 v3, v3, v4
	v_sub_f32_e32 v4, v6, v5
	s_waitcnt lgkmcnt(1)
	v_add_f32_e32 v4, v4, v7
	ds_write2st64_b32 v194, v3, v4 offset1:1
	s_and_saveexec_b64 s[4:5], s[6:7]
	s_cbranch_execz .LBB0_2747
	s_waitcnt lgkmcnt(1)
	v_max_f32_e32 v2, v2, v2
	v_max_f32_e32 v0, v0, v0
	v_max_f32_e32 v0, v0, v2
	v_mov_b32_e32 v2, s42
	v_readlane_b32 s11, v245, 38
	ds_write_b32 v2, v0
	s_nop 0
	v_mov_b32_e32 v0, s11
	ds_write_b128 v0, v[232:235]

; #define LAS __attribute__((address_space(3)))
; __device__ __forceinline__ float bf2f(unsigned short u) { return __uint_as_float((unsigned)u << 16); }
; template <int DQK, bool FOX>
; __device__ __forceinline__ void causal_attn_phase(LAS unsigned char* lds, const bf16_t* Q, int qpitch, const bf16_t* K1, const bf16_t* K2, const bf16_t* V, bf16_t* O, const float* cum2, const float* rope_cs_tab, const float* fox_ct) {
;     ...
;         const float cq = FOX ? (cum2[head * T + qrow] + offs[qrow >> 6]) * LOG2E : 0.f;
;         f32x16 o[4];
; #pragma unroll
;         for (int db = 0; db < 4; ++db)
; #pragma unroll
;             for (int r = 0; r < 16; ++r) o[db][r] = 0.f;
;         float m = -1e30f, l = 0.f;
;     ...
;             float qn = 0.f;
; #pragma unroll
;             for (int ks = 0; ks < NKS; ++ks)
; #pragma unroll
;                 for (int j = 0; j < 8; ++j) { const float a = bf2f((unsigned short)qf[ks][j]); qn += a * a; }
;             qn += __shfl_xor(qn, 32);
;             qn = sqrtf(qn) * offs[128] * 1.02f + 1.0f;
;             volatile LAS int* dflag = (volatile LAS int*)(offs + 136);
;             bool done = false;
;             CA_GLOAD(NT - 1); CA_LSTORE(0); __syncthreads();
;             for (int tt = 0; tt < NT; ++tt) {
.LBB0_2750:
	s_or_b64 exec, exec, s[4:5]
	v_add_u32_e32 v4, v197, v221
	s_waitcnt vmcnt(3)
	ds_write_b128 v224, v[160:163]
	s_waitcnt vmcnt(2)
	ds_write_b128 v225, v[164:167]
	s_waitcnt vmcnt(1)
	ds_write_b128 v4, v[168:171] offset:17408
	v_add_u32_e32 v4, v197, v222
	s_waitcnt vmcnt(0)
	ds_write_b128 v4, v[172:175] offset:17408
	s_and_saveexec_b64 s[4:5], s[44:45]
	v_add_u32_e32 v4, 0, v198
	ds_write_b32 v4, v187 offset:37888
	s_or_b64 exec, exec, s[4:5]
	s_waitcnt lgkmcnt(5)
	v_add_f32_e32 v0, v0, v3
	s_mov_b32 s4, 0xf800000
	v_mul_f32_e32 v3, 0x4f800000, v0
	v_cmp_gt_f32_e32 vcc, s4, v0
	s_mov_b32 s4, 0x3f828f5c
	v_mov_b32_e32 v14, v1
	v_cndmask_b32_e32 v0, v0, v3, vcc
	v_sqrt_f32_e32 v3, v0
	v_mov_b32_e32 v15, v1
	v_mov_b32_e32 v6, v1
	v_mov_b32_e32 v7, v1
	v_add_u32_e32 v4, -1, v3
	v_fma_f32 v5, -v4, v3, v0
	v_cmp_ge_f32_e64 s[56:57], 0, v5
	v_add_u32_e32 v5, 1, v3
	v_mov_b32_e32 v8, v1
	v_cndmask_b32_e64 v4, v3, v4, s[56:57]
	v_fma_f32 v3, -v5, v3, v0
	v_cmp_lt_f32_e64 s[56:57], 0, v3
	v_mov_b32_e32 v9, v1
	v_mov_b32_e32 v10, v1
	v_cndmask_b32_e64 v3, v4, v5, s[56:57]
	v_mul_f32_e32 v4, 0x37800000, v3
	v_cndmask_b32_e32 v3, v3, v4, vcc
	v_cmp_class_f32_e32 vcc, v0, v226
	v_mov_b32_e32 v4, v1
	v_mov_b32_e32 v5, v1
	v_cndmask_b32_e32 v0, v3, v0, vcc
	s_waitcnt lgkmcnt(4)
	v_mul_f32_e32 v0, v2, v0
	v_fma_f32 v189, v0, s4, 1.0
	s_and_b32 s4, s2, 15
	s_cmpk_lt_u32 s2, 0x100
	s_cbranch_scc1 .Lfox_h0
	s_xor_b32 s4, s4, 15
.Lfox_h0:
	v_lshl_add_u32 v228, s4, 13, v177
	s_lshl_b32 s4, s8, 4
	s_add_i32 s4, s4, 0
	v_mov_b32_e32 v0, v1
	v_mov_b32_e32 v2, v1
	v_mov_b32_e32 v3, v1
	v_mov_b32_e32 v11, v1
	v_mov_b32_e32 v12, v1
	v_mov_b32_e32 v13, v1
	v_mov_b64_e32 v[64:65], v[14:15]
	v_mov_b64_e32 v[48:49], v[14:15]
	v_mov_b64_e32 v[32:33], v[14:15]
	s_add_i32 s48, s4, 0x12a08
	s_lshl_b32 s4, s8, 2
	v_mov_b64_e32 v[62:63], v[12:13]
	v_mov_b64_e32 v[60:61], v[10:11]
	v_mov_b64_e32 v[58:59], v[8:9]
	v_mov_b64_e32 v[56:57], v[6:7]
	v_mov_b64_e32 v[54:55], v[4:5]
	v_mov_b64_e32 v[52:53], v[2:3]
	v_mov_b64_e32 v[50:51], v[0:1]
	v_mov_b64_e32 v[46:47], v[12:13]
	v_mov_b64_e32 v[44:45], v[10:11]
	v_mov_b64_e32 v[42:43], v[8:9]
	v_mov_b64_e32 v[40:41], v[6:7]
	v_mov_b64_e32 v[38:39], v[4:5]
	v_mov_b64_e32 v[36:37], v[2:3]
	v_mov_b64_e32 v[34:35], v[0:1]
	v_mov_b64_e32 v[30:31], v[12:13]
	v_mov_b64_e32 v[28:29], v[10:11]
	v_mov_b64_e32 v[26:27], v[8:9]
	v_mov_b64_e32 v[24:25], v[6:7]
	v_mov_b64_e32 v[22:23], v[4:5]
	v_mov_b64_e32 v[20:21], v[2:3]
	v_mov_b64_e32 v[18:19], v[0:1]
	v_mov_b64_e32 v[16:17], v[14:15]
	s_mov_b32 s87, 1
	s_or_b32 s46, s35, 31
	s_add_i32 s47, s9, 0x80
	s_or_b32 s24, s4, 2
	v_mov_b32_e32 v229, 0
	v_mov_b32_e32 v231, 0xf149f2ca
	s_mov_b64 s[4:5], 0
	v_mov_b32_e32 v230, v223
	v_mov_b64_e32 v[14:15], v[12:13]
	v_mov_b64_e32 v[12:13], v[10:11]
	v_mov_b64_e32 v[10:11], v[8:9]
	v_mov_b64_e32 v[8:9], v[6:7]
	v_mov_b64_e32 v[6:7], v[4:5]
	v_mov_b64_e32 v[4:5], v[2:3]
	v_mov_b64_e32 v[2:3], v[0:1]
	s_waitcnt lgkmcnt(0)
	s_barrier
	s_branch .LBB0_2755
